# v33 + tile-order division by the fixed group size 8 replaced by shift/mask in each GEMM tile header; bit-identical
# baseline (speedup 1.0000x reference)
;     __host__ __device__ bool next(int i, Unit& u) const {
;         const long L = (long)i * G + c; if (L >= nwg) return false;
;         int wgid = (int)L; { const int q = nwg / NXCD, r = nwg % NXCD, xcd = wgid % NXCD, off = wgid / NXCD; wgid = (xcd < r ? xcd * (q + 1) : r * (q + 1) + (xcd - r) * q) + off; }
;         const int nig = WGM * nN, gid = wgid / nig, fm = gid * WGM, gsz = (nM - fm) < WGM ? (nM - fm) : WGM;
;         u.pm = fm + ((wgid % nig) % gsz); u.pn = (wgid % nig) / gsz; return true;
;     }
; template <class Epi, class Sched, bool ALIGN_EPI = false, bool SP2 = false>
; __device__ __forceinline__ void gemm_phase(PG8_LAS unsigned char* lds, const Gemm g, const Sched& S, const Epi& E) {
;     ...
;         const bool has_next = S.next(ui + 1, nxt);
;         const char* nA = has_next ? (const char*)g.A + (size_t)nxt.pm * tstepA : cA; const char* nB = has_next ? (const char*)g.Bt + (size_t)nxt.pn * tstep : cB;
.LBB0_193:
	v_add_u32_e32 v244, 0x10000, v143
	v_add_u32_e32 v245, 0x14000, v143
	ds_read_b128 v[138:141], v244
	ds_read_b128 v[146:149], v244 offset:1024
	ds_read_b128 v[150:153], v244 offset:2048
	ds_read_b128 v[154:157], v244 offset:3072
	ds_read_b128 v[158:161], v245
	ds_read_b128 v[162:165], v245 offset:1024
	ds_read_b128 v[170:173], v245 offset:2048
	ds_read_b128 v[188:191], v245 offset:3072
	ds_read_b128 v[192:195], v145
	ds_read_b128 v[196:199], v145 offset:1024
	ds_read_b128 v[200:203], v145 offset:2048
	ds_read_b128 v[204:207], v145 offset:3072
	ds_read_b128 v[208:211], v145 offset:4096
	ds_read_b128 v[212:215], v145 offset:5120
	ds_read_b128 v[216:219], v145 offset:6144
	ds_read_b128 v[220:223], v145 offset:7168
	s_add_i32 s51, s51, 1
	s_mul_i32 s25, s51, s11
	s_mul_hi_u32 s27, s51, s10
	s_add_i32 s27, s27, s25
	s_mul_i32 s25, s51, s10
	s_add_u32 s38, s25, s93
	s_addc_u32 s39, s27, s9
	v_mov_b64_e32 v[0:1], 0x600
	v_cmp_lt_i64_e64 s[36:37], s[38:39], v[0:1]
	v_mov_b64_e32 v[0:1], 0x5ff
	v_cmp_gt_i64_e32 vcc, s[38:39], v[0:1]
	s_cbranch_vccnz .LBB0_195
	s_ashr_i32 s24, s38, 31
	s_lshr_b32 s24, s24, 29
	s_add_i32 s24, s38, s24
	s_ashr_i32 s25, s24, 3
	s_and_b32 s24, s24, -8
	s_sub_i32 s24, s38, s24
	s_cmp_lt_i32 s24, 0
	s_movk_i32 s26, 0xc1
	s_cselect_b32 s26, s26, 0xc0
	s_mul_i32 s24, s24, s26
	s_add_i32 s24, s24, s25
	s_mul_hi_i32 s25, s24, 0x2aaaaaab
	s_lshr_b32 s26, s25, 31
	s_ashr_i32 s25, s25, 3
	s_add_i32 s25, s25, s26
	s_lshl_b32 s26, s25, 3
	s_sub_i32 s27, 0x100, s26
	s_min_i32 s27, s27, 8
	s_mul_i32 s25, s25, 48
	s_sub_i32 s25, s24, s25
	s_ashr_i32 s24, s25, 3
	s_and_b32 s25, s25, 7
	s_add_i32 s26, s26, s25

;     __host__ __device__ bool next(int i, Unit& u) const {
;         const long L = (long)i * G + c; if (L >= nwg) return false;
;         int wgid = (int)L; { const int q = nwg / NXCD, r = nwg % NXCD, xcd = wgid % NXCD, off = wgid / NXCD; wgid = (xcd < r ? xcd * (q + 1) : r * (q + 1) + (xcd - r) * q) + off; }
;         const int nig = WGM * nN, gid = wgid / nig, fm = gid * WGM, gsz = (nM - fm) < WGM ? (nM - fm) : WGM;
;         u.pm = fm + ((wgid % nig) % gsz); u.pn = (wgid % nig) / gsz; return true;
;     }
; template <class Epi, class Sched, bool ALIGN_EPI = false, bool SP2 = false>
; __device__ __forceinline__ void gemm_phase(PG8_LAS unsigned char* lds, const Gemm g, const Sched& S, const Epi& E) {
;     ...
;         const bool has_next = S.next(ui + 1, nxt);
;         const char* nA = has_next ? (const char*)g.A + (size_t)nxt.pm * tstepA : cA; const char* nB = has_next ? (const char*)g.Bt + (size_t)nxt.pn * tstep : cB;
.LBB0_431:
	v_add_u32_e32 v244, 0x10000, v143
	v_add_u32_e32 v245, 0x14000, v143
	ds_read_b128 v[138:141], v244
	ds_read_b128 v[146:149], v244 offset:1024
	ds_read_b128 v[150:153], v244 offset:2048
	ds_read_b128 v[154:157], v244 offset:3072
	ds_read_b128 v[158:161], v245
	ds_read_b128 v[162:165], v245 offset:1024
	ds_read_b128 v[188:191], v245 offset:2048
	ds_read_b128 v[192:195], v245 offset:3072
	ds_read_b128 v[196:199], v145
	ds_read_b128 v[200:203], v145 offset:1024
	ds_read_b128 v[204:207], v145 offset:2048
	ds_read_b128 v[208:211], v145 offset:3072
	ds_read_b128 v[212:215], v145 offset:4096
	ds_read_b128 v[216:219], v145 offset:5120
	ds_read_b128 v[220:223], v145 offset:6144
	ds_read_b128 v[234:237], v145 offset:7168
	s_add_i32 s51, s51, 1
	s_mul_i32 s27, s51, s11
	s_mul_hi_u32 s36, s51, s10
	s_add_i32 s36, s36, s27
	s_mul_i32 s27, s51, s10
	s_add_u32 s42, s27, s93
	s_addc_u32 s43, s36, s9
	v_cmp_gt_i64_e32 vcc, s[42:43], v[176:177]
	v_cmp_lt_i64_e64 s[36:37], s[42:43], v[174:175]
	s_cbranch_vccnz .LBB0_433
	s_ashr_i32 s26, s42, 31
	s_lshr_b32 s26, s26, 29
	s_add_i32 s26, s42, s26
	s_ashr_i32 s27, s26, 3
	s_and_b32 s26, s26, -8
	s_sub_i32 s26, s42, s26
	s_cmp_lt_i32 s26, 0
	s_movk_i32 s40, 0x161
	s_cselect_b32 s40, s40, 0x160
	s_mul_i32 s26, s26, s40
	s_add_i32 s26, s26, s27
	s_mul_hi_i32 s27, s26, 0x2e8ba2e9
	s_lshr_b32 s40, s27, 31
	s_ashr_i32 s27, s27, 4
	s_add_i32 s27, s27, s40
	s_lshl_b32 s40, s27, 3
	s_sub_i32 s41, 0x100, s40
	s_min_i32 s41, s41, 8
	s_mulk_i32 s27, 0x58
	s_sub_i32 s27, s26, s27
	s_ashr_i32 s26, s27, 3
	s_and_b32 s27, s27, 7
	s_add_i32 s40, s40, s27

;     __host__ __device__ bool next(int i, Unit& u) const {
;     ...
;         int wgid = (int)L; { const int q = nwg / NXCD, r = nwg % NXCD, xcd = wgid % NXCD, off = wgid / NXCD; wgid = (xcd < r ? xcd * (q + 1) : r * (q + 1) + (xcd - r) * q) + off; }
;         const int nig = WGM * nN, gid = wgid / nig, fm = gid * WGM, gsz = (nM - fm) < WGM ? (nM - fm) : WGM;
;         u.pm = fm + ((wgid % nig) % gsz); u.pn = (wgid % nig) / gsz; return true;
.LBB0_731:
	s_ashr_i32 s5, s5, 3
	s_add_i32 s5, s7, s5
	s_ashr_i32 s6, s5, 31
	s_lshr_b32 s6, s6, 27
	s_add_i32 s6, s5, s6
	s_ashr_i32 s7, s6, 5
	s_lshl_b32 s7, s7, 3
	s_sub_i32 s50, 0x100, s7
	s_min_i32 s51, s50, 8
	s_andn2_b32 s6, s6, 31
	s_sub_i32 s5, s5, s6
	s_ashr_i32 s50, s5, 3
	s_and_b32 s5, s5, 7
	s_add_i32 s52, s7, s5

;     __host__ __device__ bool next(int i, Unit& u) const {
;         const long L = (long)i * G + c; if (L >= nwg) return false;
;         int wgid = (int)L; { const int q = nwg / NXCD, r = nwg % NXCD, xcd = wgid % NXCD, off = wgid / NXCD; wgid = (xcd < r ? xcd * (q + 1) : r * (q + 1) + (xcd - r) * q) + off; }
;         const int nig = WGM * nN, gid = wgid / nig, fm = gid * WGM, gsz = (nM - fm) < WGM ? (nM - fm) : WGM;
;         u.pm = fm + ((wgid % nig) % gsz); u.pn = (wgid % nig) / gsz; return true;
;     }
; template <class Epi, class Sched, bool ALIGN_EPI = false, bool SP2 = false>
; __device__ __forceinline__ void gemm_phase(PG8_LAS unsigned char* lds, const Gemm g, const Sched& S, const Epi& E) {
;     ...
;         const bool has_next = S.next(ui + 1, nxt);
;         const char* nA = has_next ? (const char*)g.A + (size_t)nxt.pm * tstepA : cA; const char* nB = has_next ? (const char*)g.Bt + (size_t)nxt.pn * tstep : cB;
.LBB0_833:
	v_add_u32_e32 v244, 0x10000, v142
	v_add_u32_e32 v245, 0x14000, v142
	ds_read_b128 v[144:147], v244
	ds_read_b128 v[148:151], v244 offset:1024
	ds_read_b128 v[152:155], v244 offset:2048
	ds_read_b128 v[156:159], v244 offset:3072
	ds_read_b128 v[160:163], v245
	ds_read_b128 v[164:167], v245 offset:1024
	ds_read_b128 v[170:173], v245 offset:2048
	ds_read_b128 v[188:191], v245 offset:3072
	ds_read_b128 v[192:195], v143
	ds_read_b128 v[196:199], v143 offset:1024
	ds_read_b128 v[200:203], v143 offset:2048
	ds_read_b128 v[204:207], v143 offset:3072
	ds_read_b128 v[208:211], v143 offset:4096
	ds_read_b128 v[212:215], v143 offset:5120
	ds_read_b128 v[216:219], v143 offset:6144
	ds_read_b128 v[220:223], v143 offset:7168
	s_add_i32 s58, s58, 1
	s_mul_i32 s38, s58, s11
	s_mul_hi_u32 s39, s58, s10
	s_add_i32 s39, s39, s38
	s_mul_i32 s38, s58, s10
	s_add_u32 s44, s38, s93
	s_addc_u32 s45, s39, s9
	v_cmp_gt_i64_e32 vcc, s[44:45], v[186:187]
	v_cmp_lt_i64_e64 s[38:39], s[44:45], v[184:185]
	s_cbranch_vccnz .LBB0_835
	s_ashr_i32 s40, s44, 31
	s_lshr_b32 s40, s40, 29
	s_add_i32 s40, s44, s40
	s_ashr_i32 s41, s40, 3
	s_and_b32 s40, s40, -8
	s_sub_i32 s40, s44, s40
	s_cmp_lt_i32 s40, 0
	s_movk_i32 s36, 0x2c1
	s_cselect_b32 s42, s36, 0x2c0
	s_mul_i32 s40, s40, s42
	s_add_i32 s40, s40, s41
	s_mul_hi_i32 s41, s40, 0x2e8ba2e9
	s_lshr_b32 s42, s41, 31
	s_ashr_i32 s41, s41, 5
	s_add_i32 s41, s41, s42
	s_lshl_b32 s42, s41, 3
	s_sub_i32 s43, 0x100, s42
	s_min_i32 s43, s43, 8
	s_mulk_i32 s41, 0xb0
	s_sub_i32 s41, s40, s41
	s_ashr_i32 s40, s41, 3
	s_and_b32 s41, s41, 7
	s_add_i32 s42, s42, s41

;     __host__ __device__ bool next(int i, Unit& u) const {
;     ...
;         int wgid = (int)L; { const int q = nwg / NXCD, r = nwg % NXCD, xcd = wgid % NXCD, off = wgid / NXCD; wgid = (xcd < r ? xcd * (q + 1) : r * (q + 1) + (xcd - r) * q) + off; }
;         const int nig = WGM * nN, gid = wgid / nig, fm = gid * WGM, gsz = (nM - fm) < WGM ? (nM - fm) : WGM;
;         u.pm = fm + ((wgid % nig) % gsz); u.pn = (wgid % nig) / gsz; return true;
.LBB0_907:
	s_ashr_i32 s5, s5, 3
	s_add_i32 s5, s7, s5
	s_ashr_i32 s6, s5, 31
	s_lshr_b32 s6, s6, 27
	s_add_i32 s6, s5, s6
	s_ashr_i32 s7, s6, 5
	s_lshl_b32 s7, s7, 3
	s_sub_i32 s38, 0x100, s7
	s_min_i32 s38, s38, 8
	s_andn2_b32 s6, s6, 31
	s_sub_i32 s5, s5, s6
	s_ashr_i32 s84, s5, 3
	s_and_b32 s5, s5, 7
	s_add_i32 s85, s7, s5

;     __host__ __device__ bool next(int i, Unit& u) const {
;     ...
;         int wgid = (int)L; { const int q = nwg / NXCD, r = nwg % NXCD, xcd = wgid % NXCD, off = wgid / NXCD; wgid = (xcd < r ? xcd * (q + 1) : r * (q + 1) + (xcd - r) * q) + off; }
;         const int nig = WGM * nN, gid = wgid / nig, fm = gid * WGM, gsz = (nM - fm) < WGM ? (nM - fm) : WGM;
;         u.pm = fm + ((wgid % nig) % gsz); u.pn = (wgid % nig) / gsz; return true;
.LBB0_968:
	s_ashr_i32 s5, s5, 3
	s_add_i32 s5, s7, s5
	s_ashr_i32 s6, s5, 31
	s_lshr_b32 s6, s6, 27
	s_add_i32 s6, s5, s6
	s_ashr_i32 s7, s6, 5
	s_lshl_b32 s7, s7, 3
	s_sub_i32 s36, 0x100, s7
	s_min_i32 s36, s36, 8
	s_andn2_b32 s6, s6, 31
	s_sub_i32 s5, s5, s6
	s_ashr_i32 s93, s5, 3
	s_and_b32 s5, s5, 7
	s_add_i32 s75, s7, s5
